# XCD-group barriers (run-time verified placement, full-barrier fallback) at the five phase boundaries with group-local dependences
# speedup vs baseline: 1.0766x; 1.0071x over previous
_Z10fwd_kernel4Args:
	v_writelane_b32 v255, 0, 23
	v_writelane_b32 v255, 0, 24
	s_load_dwordx4 s[68:71], s[0:1], 0xb0
	s_load_dwordx2 s[46:47], s[0:1], 0xc0
	s_add_u32 s4, s0, 0xc0
	s_addc_u32 s5, s1, 0
	v_and_b32_e32 v137, 0x3ff, v0
	v_writelane_b32 v254, s4, 0
	v_cmp_gt_u32_e32 vcc, 16, v137
	s_nop 0
	v_writelane_b32 v254, s5, 1
	s_and_saveexec_b64 s[6:7], vcc
	v_lshl_add_u32 v1, v137, 2, 0
	v_add_u32_e32 v1, 0x257c0, v1
	v_mov_b32_e32 v2, 0
	ds_write_b32 v1, v2
	s_or_b64 exec, exec, s[6:7]
	s_waitcnt lgkmcnt(0)
	s_barrier
	s_load_dwordx2 s[74:75], s[0:1], 0xa8
	s_cmp_lg_u32 s70, 0
	s_mov_b32 s8, 0
	s_cselect_b64 s[52:53], -1, 0
	s_cmp_eq_u32 s70, 0
	v_cmp_eq_u32_e32 vcc, 0, v137
	s_cbranch_scc1 .LBB0_7
	s_getreg_b32 s3, hwreg(HW_REG_XCC_ID, 0, 4)
	s_and_b32 s8, s3, 15
	s_and_saveexec_b64 s[10:11], vcc
	s_cbranch_execz .LBB0_6
	s_mov_b64 s[4:5], exec
	v_mbcnt_lo_u32_b32 v1, s4, 0
	v_mbcnt_hi_u32_b32 v1, s5, v1
	v_cmp_eq_u32_e32 vcc, 0, v1
	s_and_b64 s[6:7], exec, vcc
	s_mov_b64 exec, s[6:7]
	s_cbranch_execz .LBB0_6
	s_lshl_b32 s3, s8, 8
	s_bcnt1_i32_b64 s4, s[4:5]
	v_mov_b32_e32 v1, s3
	v_mov_b32_e32 v2, s4
	s_waitcnt lgkmcnt(0)
	s_and_b32 s3, s2, 7
	s_lshl_b32 s3, s3, 6
	s_add_i32 s3, s3, 0x3600
	v_mov_b32_e32 v3, s3
	s_lshl_b32 s4, 1, s8
	v_mov_b32_e32 v4, s4
	global_atomic_or v4, v3, v4, s[74:75] sc0
	s_waitcnt vmcnt(0)
	global_atomic_add v1, v2, s[74:75] offset:1024

.LBB0_603:
	s_sub_i32 s3, s68, 1
	s_lshl_b32 s16, 1, s3
	s_and_b32 s16, s16, 0x18b0
	s_cmp_eq_u32 s16, 0
	s_cbranch_scc1 .Lmy_xbA
	v_readlane_b32 s18, v255, 24
	s_cmp_lg_u32 s18, 0
	s_cbranch_scc1 .Lmy_xbG_known
	s_add_u32 s16, s74, 0x3600
	s_addc_u32 s17, s75, 0
	global_load_dword v4, v163, s[16:17] sc1
	global_load_dword v5, v163, s[16:17] offset:64 sc1
	global_load_dword v6, v163, s[16:17] offset:128 sc1
	global_load_dword v7, v163, s[16:17] offset:192 sc1
	global_load_dword v8, v163, s[16:17] offset:256 sc1
	global_load_dword v9, v163, s[16:17] offset:320 sc1
	global_load_dword v10, v163, s[16:17] offset:384 sc1
	global_load_dword v11, v163, s[16:17] offset:448 sc1
	s_waitcnt vmcnt(0)
	v_add_u32_e32 v12, -1, v4
	v_add_u32_e32 v13, -1, v5
	v_add_u32_e32 v14, -1, v6
	v_add_u32_e32 v15, -1, v7
	v_add_u32_e32 v16, -1, v8
	v_add_u32_e32 v17, -1, v9
	v_add_u32_e32 v18, -1, v10
	v_add_u32_e32 v19, -1, v11
	v_and_b32_e32 v12, v12, v4
	v_and_b32_e32 v13, v13, v5
	v_and_b32_e32 v14, v14, v6
	v_and_b32_e32 v15, v15, v7
	v_and_b32_e32 v16, v16, v8
	v_and_b32_e32 v17, v17, v9
	v_and_b32_e32 v18, v18, v10
	v_and_b32_e32 v19, v19, v11
	v_or3_b32 v12, v12, v13, v14
	v_or3_b32 v15, v15, v16, v17
	v_or3_b32 v12, v12, v15, v18
	v_or_b32_e32 v12, v12, v19
	v_min_u32_e32 v4, v4, v5
	v_min_u32_e32 v6, v6, v7
	v_min_u32_e32 v8, v8, v9
	v_min_u32_e32 v10, v10, v11
	v_min_u32_e32 v4, v4, v6
	v_min_u32_e32 v8, v8, v10
	v_min_u32_e32 v4, v4, v8
	v_readfirstlane_b32 s16, v12
	v_readfirstlane_b32 s17, v4
	s_cmp_eq_u32 s16, 0
	s_cselect_b32 s18, 2, 1
	s_cmp_eq_u32 s17, 0
	s_cselect_b32 s18, 1, s18
	s_nop 3
	v_writelane_b32 v255, s18, 24
.Lmy_xbG_known:
	s_cmp_eq_u32 s18, 2
	s_cbranch_scc0 .Lmy_xbA
	s_and_b32 s3, s2, 7
	s_lshl_b32 s3, s3, 8
	s_add_u32 s16, s74, s3
	s_addc_u32 s17, s75, 0
	s_add_u32 s16, s16, 0x2400
	s_addc_u32 s17, s17, 0
	v_readlane_b32 s18, v255, 23
	s_add_i32 s18, s18, 1
	s_nop 3
	v_writelane_b32 v255, s18, 23
	s_lshl_b32 s18, s18, 5
	v_mov_b32_e32 v4, s18
	global_atomic_add v163, v212, s[16:17]
	buffer_inv sc1
	s_mov_b32 s3, 0
.Lmy_xbG_spin:
	global_load_dword v5, v163, s[16:17] sc1
	s_waitcnt vmcnt(0)
	v_cmp_ge_u32_e32 vcc, v5, v4
	s_cbranch_vccnz .LBB0_10
	s_add_i32 s3, s3, 1
	s_cmp_lt_u32 s3, 0x20000
	s_cbranch_scc1 .Lmy_xbG_spin
	s_branch .LBB0_10
